# phase-13 K-loop: every MFMA run 8-byte aligned (3 s_nop in load segments + 1 after the loop)
# baseline (speedup 1.0000x reference)
; #define PG8_STAGE(bufoff, gbase, voff) do { _Pragma("unroll") for (int _i = 0; _i < 2; ++_i) \
;         __builtin_amdgcn_global_load_lds((const unsigned*)((const char*)(gbase) + (voff)[_i]), (PG8_LAS unsigned*)(lds + (bufoff) + ldsw + _i * 8192), 16, 0, 0); } while (0)
; #define PG8_LDA(dst, b, h) do { _Pragma("unroll") for (int m = 0; m < 4; ++m) _Pragma("unroll") for (int k = 0; k < 2; ++k) dst[m][k] = *(const PG8_LAS bf16x8*)(lds + PG8_SA(b, h) + aoff + m * 2048 + k * 1024); } while (0)
; #define PG8_LDB(dst, b, h) do { _Pragma("unroll") for (int n = 0; n < 2; ++n) _Pragma("unroll") for (int k = 0; k < 2; ++k) dst[n][k] = *(const PG8_LAS bf16x8*)(lds + PG8_SB(b, h) + boff + n * 2048 + k * 1024); } while (0)
; #define PG8_MMA(ai, bj, At, Bt) do { __builtin_amdgcn_s_setprio(1); _Pragma("unroll") for (int m = 0; m < 4; ++m) _Pragma("unroll") for (int n = 0; n < 2; ++n) _Pragma("unroll") for (int k = 0; k < 2; ++k) \
;         acc[ai][bj][m][n] = __builtin_amdgcn_mfma_f32_16x16x32_bf16(Bt[n][k], At[m][k], acc[ai][bj][m][n], 0, 0, 0); __builtin_amdgcn_s_setprio(0); } while (0)
; #define PG8_WAIT_V(n) asm volatile("s_waitcnt vmcnt(" #n ")" ::: "memory")
; #define PG8_WAIT_L(n) asm volatile("s_waitcnt lgkmcnt(" #n ")" ::: "memory")
; #define PG8_BAR __builtin_amdgcn_s_barrier()
; #define PG8_SCHED __builtin_amdgcn_sched_barrier(0)
; template <class Epi, class Sched, bool ALIGN_EPI = false, bool SP2 = false>
; __device__ __forceinline__ void gemm_phase(PG8_LAS unsigned char* lds, const Gemm g, const Sched& S, const Epi& E) {
;     ...
;             PG8_LDB(B0, 0, 0); PG8_LDB(B1, 0, 1); PG8_SCHED; PG8_LDA(At, 0, 0); PG8_STAGE(PG8_SA(1, 1), a1 + hstep, voffA);
;             PG8_WAIT_V(8); PG8_WAIT_L(0); PG8_BAR; PG8_MMA(0, 0, At, B0); PG8_MMA(0, 1, At, B1); PG8_BAR; PG8_SCHED;
;             PG8_LDA(At, 0, 1); PG8_STAGE(PG8_SB(0, 0), b2, voffB); PG8_STAGE(PG8_SB(0, 1), b2 + hstep, voffB); PG8_STAGE(PG8_SA(0, 0), a2, voffA);
;             PG8_WAIT_V(8); PG8_WAIT_L(0); PG8_BAR; PG8_MMA(1, 0, At, B0); PG8_MMA(1, 1, At, B1); PG8_BAR; PG8_SCHED;
.LBB0_2271:
	ds_read_b128 v[144:147], v160
	ds_read_b128 v[148:151], v160 offset:1024
	ds_read_b128 v[152:155], v160 offset:2048
	ds_read_b128 v[166:169], v160 offset:3072
	ds_read_b128 v[170:173], v161
	ds_read_b128 v[174:177], v161 offset:1024
	ds_read_b128 v[178:181], v161 offset:2048
	ds_read_b128 v[182:185], v161 offset:3072
	s_add_u32 s26, s24, 0xfff50080
	s_addc_u32 s27, s25, -1
	s_cmp_eq_u32 s55, 40
	s_cselect_b32 s29, s3, s27
	s_cselect_b32 s28, s2, s26
	s_cselect_b32 s27, s23, s54
	s_cselect_b32 s26, s22, s53
	v_lshl_add_u64 v[156:157], s[24:25], 0, v[136:137]
	s_add_i32 m0, s36, 0xc000
	ds_read_b128 v[186:189], v162
	ds_read_b128 v[190:193], v162 offset:1024
	ds_read_b128 v[194:197], v162 offset:2048
	ds_read_b128 v[198:201], v162 offset:3072
	ds_read_b128 v[202:205], v162 offset:4096
	ds_read_b128 v[206:209], v162 offset:5120
	ds_read_b128 v[210:213], v162 offset:6144
	ds_read_b128 v[214:217], v162 offset:7168
	global_load_lds_dwordx4 v[156:157], off
	v_lshl_add_u64 v[156:157], s[24:25], 0, v[138:139]
	s_add_i32 m0, s36, 0xe000
	s_nop 0
	global_load_lds_dwordx4 v[156:157], off
	s_nop 0
	s_waitcnt vmcnt(8)
	s_waitcnt lgkmcnt(0)
	s_barrier
	s_setprio 1
	s_waitcnt lgkmcnt(0)
	v_mfma_f32_16x16x32_bf16 v[124:127], v[144:147], v[186:189], v[124:127]
	v_mfma_f32_16x16x32_bf16 v[120:123], v[152:155], v[186:189], v[120:123]
	v_mfma_f32_16x16x32_bf16 v[108:111], v[144:147], v[194:197], v[108:111]
	v_mfma_f32_16x16x32_bf16 v[104:107], v[152:155], v[194:197], v[104:107]
	v_mfma_f32_16x16x32_bf16 v[92:95], v[144:147], v[202:205], v[92:95]
	v_mfma_f32_16x16x32_bf16 v[88:91], v[152:155], v[202:205], v[88:91]
	v_mfma_f32_16x16x32_bf16 v[76:79], v[144:147], v[210:213], v[76:79]
	v_mfma_f32_16x16x32_bf16 v[72:75], v[152:155], v[210:213], v[72:75]
	v_mfma_f32_16x16x32_bf16 v[124:127], v[148:151], v[190:193], v[124:127]
	v_mfma_f32_16x16x32_bf16 v[120:123], v[166:169], v[190:193], v[120:123]
	v_mfma_f32_16x16x32_bf16 v[108:111], v[148:151], v[198:201], v[108:111]
	v_mfma_f32_16x16x32_bf16 v[104:107], v[166:169], v[198:201], v[104:107]
	v_mfma_f32_16x16x32_bf16 v[92:95], v[148:151], v[206:209], v[92:95]
	v_mfma_f32_16x16x32_bf16 v[88:91], v[166:169], v[206:209], v[88:91]
	v_mfma_f32_16x16x32_bf16 v[76:79], v[148:151], v[214:217], v[76:79]
	v_mfma_f32_16x16x32_bf16 v[72:75], v[166:169], v[214:217], v[72:75]
	s_setprio 0
	s_setprio 1
	v_mfma_f32_16x16x32_bf16 v[116:119], v[170:173], v[186:189], v[116:119]
	v_mfma_f32_16x16x32_bf16 v[112:115], v[178:181], v[186:189], v[112:115]
	v_mfma_f32_16x16x32_bf16 v[100:103], v[170:173], v[194:197], v[100:103]
	v_mfma_f32_16x16x32_bf16 v[96:99], v[178:181], v[194:197], v[96:99]
	v_mfma_f32_16x16x32_bf16 v[84:87], v[170:173], v[202:205], v[84:87]
	v_mfma_f32_16x16x32_bf16 v[80:83], v[178:181], v[202:205], v[80:83]
	v_mfma_f32_16x16x32_bf16 v[68:71], v[170:173], v[210:213], v[68:71]
	v_mfma_f32_16x16x32_bf16 v[64:67], v[178:181], v[210:213], v[64:67]
	v_mfma_f32_16x16x32_bf16 v[116:119], v[174:177], v[190:193], v[116:119]
	v_mfma_f32_16x16x32_bf16 v[112:115], v[182:185], v[190:193], v[112:115]
	v_mfma_f32_16x16x32_bf16 v[100:103], v[174:177], v[198:201], v[100:103]
	v_mfma_f32_16x16x32_bf16 v[96:99], v[182:185], v[198:201], v[96:99]
	v_mfma_f32_16x16x32_bf16 v[84:87], v[174:177], v[206:209], v[84:87]
	v_mfma_f32_16x16x32_bf16 v[80:83], v[182:185], v[206:209], v[80:83]
	v_mfma_f32_16x16x32_bf16 v[68:71], v[174:177], v[214:217], v[68:71]
	v_mfma_f32_16x16x32_bf16 v[64:67], v[182:185], v[214:217], v[64:67]
	s_setprio 0
	s_barrier
	s_add_i32 s56, s46, s35
	v_lshl_add_u64 v[156:157], s[26:27], 0, v[130:131]
	s_mov_b32 m0, s56
	ds_read_b128 v[186:189], v162 offset:16384
	ds_read_b128 v[190:193], v162 offset:17408
	ds_read_b128 v[194:197], v162 offset:18432
	ds_read_b128 v[198:201], v162 offset:19456
	ds_read_b128 v[202:205], v162 offset:20480
	ds_read_b128 v[206:209], v162 offset:21504
	ds_read_b128 v[210:213], v162 offset:22528
	ds_read_b128 v[214:217], v162 offset:23552
	global_load_lds_dwordx4 v[156:157], off
	s_add_i32 m0, s56, 0x2000
	s_add_u32 s56, s26, 0xb0000
	v_lshl_add_u64 v[218:219], s[26:27], 0, v[134:135]
	s_addc_u32 s57, s27, 0
	s_add_i32 s58, s47, s35
	global_load_lds_dwordx4 v[218:219], off
	v_lshl_add_u64 v[220:221], s[56:57], 0, v[130:131]
	s_mov_b32 m0, s58
	v_lshl_add_u64 v[222:223], s[28:29], 0, v[132:133]
	global_load_lds_dwordx4 v[220:221], off
	v_lshl_add_u64 v[220:221], s[56:57], 0, v[134:135]
	s_add_i32 m0, s58, 0x2000
	s_nop 0
	global_load_lds_dwordx4 v[220:221], off
	v_lshl_add_u64 v[220:221], s[28:29], 0, v[128:129]
	s_mov_b32 m0, s36
	s_nop 0
	global_load_lds_dwordx4 v[220:221], off
	s_mov_b32 m0, s37
	s_nop 0
	global_load_lds_dwordx4 v[222:223], off
	s_nop 0
	s_waitcnt vmcnt(8)
	s_waitcnt lgkmcnt(0)
	s_barrier
; #define PG8_STAGE(bufoff, gbase, voff) do { _Pragma("unroll") for (int _i = 0; _i < 2; ++_i) \
;         __builtin_amdgcn_global_load_lds((const unsigned*)((const char*)(gbase) + (voff)[_i]), (PG8_LAS unsigned*)(lds + (bufoff) + ldsw + _i * 8192), 16, 0, 0); } while (0)
; #define PG8_LDA(dst, b, h) do { _Pragma("unroll") for (int m = 0; m < 4; ++m) _Pragma("unroll") for (int k = 0; k < 2; ++k) dst[m][k] = *(const PG8_LAS bf16x8*)(lds + PG8_SA(b, h) + aoff + m * 2048 + k * 1024); } while (0)
; #define PG8_LDB(dst, b, h) do { _Pragma("unroll") for (int n = 0; n < 2; ++n) _Pragma("unroll") for (int k = 0; k < 2; ++k) dst[n][k] = *(const PG8_LAS bf16x8*)(lds + PG8_SB(b, h) + boff + n * 2048 + k * 1024); } while (0)
; #define PG8_MMA(ai, bj, At, Bt) do { __builtin_amdgcn_s_setprio(1); _Pragma("unroll") for (int m = 0; m < 4; ++m) _Pragma("unroll") for (int n = 0; n < 2; ++n) _Pragma("unroll") for (int k = 0; k < 2; ++k) \
;         acc[ai][bj][m][n] = __builtin_amdgcn_mfma_f32_16x16x32_bf16(Bt[n][k], At[m][k], acc[ai][bj][m][n], 0, 0, 0); __builtin_amdgcn_s_setprio(0); } while (0)
; #define PG8_WAIT_V(n) asm volatile("s_waitcnt vmcnt(" #n ")" ::: "memory")
; #define PG8_WAIT_L(n) asm volatile("s_waitcnt lgkmcnt(" #n ")" ::: "memory")
; #define PG8_BAR __builtin_amdgcn_s_barrier()
; #define PG8_SCHED __builtin_amdgcn_sched_barrier(0)
; template <class Epi, class Sched, bool ALIGN_EPI = false, bool SP2 = false>
; __device__ __forceinline__ void gemm_phase(PG8_LAS unsigned char* lds, const Gemm g, const Sched& S, const Epi& E) {
;     ...
;             PG8_WAIT_V(8); PG8_WAIT_L(0); PG8_BAR; PG8_MMA(1, 0, At, B0); PG8_MMA(1, 1, At, B1); PG8_BAR; PG8_SCHED;
;             PG8_LDB(B0, 1, 0); PG8_LDB(B1, 1, 1); PG8_SCHED; PG8_LDA(At, 1, 0); PG8_STAGE(PG8_SA(0, 1), a2 + hstep, voffA);
;             PG8_WAIT_V(8); PG8_WAIT_L(0); PG8_BAR; PG8_MMA(0, 0, At, B0); PG8_MMA(0, 1, At, B1); PG8_BAR; PG8_SCHED;
	s_setprio 1
	s_waitcnt lgkmcnt(0)
	v_mfma_f32_16x16x32_bf16 v[60:63], v[144:147], v[186:189], v[60:63]
	v_mfma_f32_16x16x32_bf16 v[56:59], v[152:155], v[186:189], v[56:59]
	v_mfma_f32_16x16x32_bf16 v[44:47], v[144:147], v[194:197], v[44:47]
	v_mfma_f32_16x16x32_bf16 v[40:43], v[152:155], v[194:197], v[40:43]
	v_mfma_f32_16x16x32_bf16 v[28:31], v[144:147], v[202:205], v[28:31]
	v_mfma_f32_16x16x32_bf16 v[24:27], v[152:155], v[202:205], v[24:27]
	v_mfma_f32_16x16x32_bf16 v[12:15], v[144:147], v[210:213], v[12:15]
	v_mfma_f32_16x16x32_bf16 v[8:11], v[152:155], v[210:213], v[8:11]
	v_mfma_f32_16x16x32_bf16 v[60:63], v[148:151], v[190:193], v[60:63]
	v_mfma_f32_16x16x32_bf16 v[56:59], v[166:169], v[190:193], v[56:59]
	v_mfma_f32_16x16x32_bf16 v[44:47], v[148:151], v[198:201], v[44:47]
	v_mfma_f32_16x16x32_bf16 v[40:43], v[166:169], v[198:201], v[40:43]
	v_mfma_f32_16x16x32_bf16 v[28:31], v[148:151], v[206:209], v[28:31]
	v_mfma_f32_16x16x32_bf16 v[24:27], v[166:169], v[206:209], v[24:27]
	v_mfma_f32_16x16x32_bf16 v[12:15], v[148:151], v[214:217], v[12:15]
	v_mfma_f32_16x16x32_bf16 v[8:11], v[166:169], v[214:217], v[8:11]
	s_setprio 0
	s_setprio 1
	v_mfma_f32_16x16x32_bf16 v[52:55], v[170:173], v[186:189], v[52:55]
	v_mfma_f32_16x16x32_bf16 v[48:51], v[178:181], v[186:189], v[48:51]
	v_mfma_f32_16x16x32_bf16 v[36:39], v[170:173], v[194:197], v[36:39]
	v_mfma_f32_16x16x32_bf16 v[32:35], v[178:181], v[194:197], v[32:35]
	v_mfma_f32_16x16x32_bf16 v[20:23], v[170:173], v[202:205], v[20:23]
	v_mfma_f32_16x16x32_bf16 v[16:19], v[178:181], v[202:205], v[16:19]
	v_mfma_f32_16x16x32_bf16 v[4:7], v[170:173], v[210:213], v[4:7]
	v_mfma_f32_16x16x32_bf16 v[0:3], v[178:181], v[210:213], v[0:3]
	v_mfma_f32_16x16x32_bf16 v[52:55], v[174:177], v[190:193], v[52:55]
	v_mfma_f32_16x16x32_bf16 v[48:51], v[182:185], v[190:193], v[48:51]
	v_mfma_f32_16x16x32_bf16 v[36:39], v[174:177], v[198:201], v[36:39]
	v_mfma_f32_16x16x32_bf16 v[32:35], v[182:185], v[198:201], v[32:35]
	v_mfma_f32_16x16x32_bf16 v[20:23], v[174:177], v[206:209], v[20:23]
	v_mfma_f32_16x16x32_bf16 v[16:19], v[182:185], v[206:209], v[16:19]
	v_mfma_f32_16x16x32_bf16 v[4:7], v[174:177], v[214:217], v[4:7]
	v_mfma_f32_16x16x32_bf16 v[0:3], v[182:185], v[214:217], v[0:3]
	s_setprio 0
	s_barrier
	ds_read_b128 v[144:147], v163
	ds_read_b128 v[148:151], v163 offset:1024
	ds_read_b128 v[152:155], v163 offset:2048
	ds_read_b128 v[166:169], v163 offset:3072
	ds_read_b128 v[170:173], v164
	ds_read_b128 v[174:177], v164 offset:1024
	ds_read_b128 v[178:181], v164 offset:2048
	ds_read_b128 v[182:185], v164 offset:3072
	s_add_u32 s28, s28, 0xb0000
	s_addc_u32 s29, s29, 0
	s_mov_b32 m0, s38
	v_lshl_add_u64 v[224:225], s[28:29], 0, v[128:129]
	ds_read_b128 v[186:189], v162 offset:32768
	ds_read_b128 v[190:193], v162 offset:33792
	ds_read_b128 v[194:197], v162 offset:34816
	ds_read_b128 v[198:201], v162 offset:35840
	ds_read_b128 v[202:205], v162 offset:36864
	ds_read_b128 v[206:209], v162 offset:37888
	ds_read_b128 v[210:213], v162 offset:38912
	ds_read_b128 v[214:217], v162 offset:39936
	global_load_lds_dwordx4 v[224:225], off
	v_lshl_add_u64 v[224:225], s[28:29], 0, v[132:133]
	s_mov_b32 m0, s39
	s_nop 0
	global_load_lds_dwordx4 v[224:225], off
	s_nop 0
	s_waitcnt vmcnt(8)
	s_waitcnt lgkmcnt(0)
	s_barrier
	s_setprio 1
	s_waitcnt lgkmcnt(0)
	v_mfma_f32_16x16x32_bf16 v[124:127], v[144:147], v[186:189], v[124:127]
	v_mfma_f32_16x16x32_bf16 v[120:123], v[152:155], v[186:189], v[120:123]
	v_mfma_f32_16x16x32_bf16 v[108:111], v[144:147], v[194:197], v[108:111]
	v_mfma_f32_16x16x32_bf16 v[104:107], v[152:155], v[194:197], v[104:107]
	v_mfma_f32_16x16x32_bf16 v[92:95], v[144:147], v[202:205], v[92:95]
	v_mfma_f32_16x16x32_bf16 v[88:91], v[152:155], v[202:205], v[88:91]
	v_mfma_f32_16x16x32_bf16 v[76:79], v[144:147], v[210:213], v[76:79]
	v_mfma_f32_16x16x32_bf16 v[72:75], v[152:155], v[210:213], v[72:75]
	v_mfma_f32_16x16x32_bf16 v[124:127], v[148:151], v[190:193], v[124:127]
	v_mfma_f32_16x16x32_bf16 v[120:123], v[166:169], v[190:193], v[120:123]
	v_mfma_f32_16x16x32_bf16 v[108:111], v[148:151], v[198:201], v[108:111]
	v_mfma_f32_16x16x32_bf16 v[104:107], v[166:169], v[198:201], v[104:107]
	v_mfma_f32_16x16x32_bf16 v[92:95], v[148:151], v[206:209], v[92:95]
	v_mfma_f32_16x16x32_bf16 v[88:91], v[166:169], v[206:209], v[88:91]
	v_mfma_f32_16x16x32_bf16 v[76:79], v[148:151], v[214:217], v[76:79]
	v_mfma_f32_16x16x32_bf16 v[72:75], v[166:169], v[214:217], v[72:75]
	s_setprio 0
	s_setprio 1
	v_mfma_f32_16x16x32_bf16 v[116:119], v[170:173], v[186:189], v[116:119]
	v_mfma_f32_16x16x32_bf16 v[112:115], v[178:181], v[186:189], v[112:115]
	v_mfma_f32_16x16x32_bf16 v[100:103], v[170:173], v[194:197], v[100:103]
	v_mfma_f32_16x16x32_bf16 v[96:99], v[178:181], v[194:197], v[96:99]
	v_mfma_f32_16x16x32_bf16 v[84:87], v[170:173], v[202:205], v[84:87]
	v_mfma_f32_16x16x32_bf16 v[80:83], v[178:181], v[202:205], v[80:83]
	v_mfma_f32_16x16x32_bf16 v[68:71], v[170:173], v[210:213], v[68:71]
	v_mfma_f32_16x16x32_bf16 v[64:67], v[178:181], v[210:213], v[64:67]
	v_mfma_f32_16x16x32_bf16 v[116:119], v[174:177], v[190:193], v[116:119]
	v_mfma_f32_16x16x32_bf16 v[112:115], v[182:185], v[190:193], v[112:115]
	v_mfma_f32_16x16x32_bf16 v[100:103], v[174:177], v[198:201], v[100:103]
	v_mfma_f32_16x16x32_bf16 v[96:99], v[182:185], v[198:201], v[96:99]
	v_mfma_f32_16x16x32_bf16 v[84:87], v[174:177], v[206:209], v[84:87]
	v_mfma_f32_16x16x32_bf16 v[80:83], v[182:185], v[206:209], v[80:83]
	v_mfma_f32_16x16x32_bf16 v[68:71], v[174:177], v[214:217], v[68:71]
	v_mfma_f32_16x16x32_bf16 v[64:67], v[182:185], v[214:217], v[64:67]
	s_setprio 0
	s_barrier
; #define PG8_STAGE(bufoff, gbase, voff) do { _Pragma("unroll") for (int _i = 0; _i < 2; ++_i) \
;         __builtin_amdgcn_global_load_lds((const unsigned*)((const char*)(gbase) + (voff)[_i]), (PG8_LAS unsigned*)(lds + (bufoff) + ldsw + _i * 8192), 16, 0, 0); } while (0)
; #define PG8_LDA(dst, b, h) do { _Pragma("unroll") for (int m = 0; m < 4; ++m) _Pragma("unroll") for (int k = 0; k < 2; ++k) dst[m][k] = *(const PG8_LAS bf16x8*)(lds + PG8_SA(b, h) + aoff + m * 2048 + k * 1024); } while (0)
; #define PG8_MMA(ai, bj, At, Bt) do { __builtin_amdgcn_s_setprio(1); _Pragma("unroll") for (int m = 0; m < 4; ++m) _Pragma("unroll") for (int n = 0; n < 2; ++n) _Pragma("unroll") for (int k = 0; k < 2; ++k) \
;         acc[ai][bj][m][n] = __builtin_amdgcn_mfma_f32_16x16x32_bf16(Bt[n][k], At[m][k], acc[ai][bj][m][n], 0, 0, 0); __builtin_amdgcn_s_setprio(0); } while (0)
; #define PG8_WAIT_V(n) asm volatile("s_waitcnt vmcnt(" #n ")" ::: "memory")
; #define PG8_WAIT_L(n) asm volatile("s_waitcnt lgkmcnt(" #n ")" ::: "memory")
; #define PG8_BAR __builtin_amdgcn_s_barrier()
; #define PG8_SCHED __builtin_amdgcn_sched_barrier(0)
; template <class Epi, class Sched, bool ALIGN_EPI = false, bool SP2 = false>
; __device__ __forceinline__ void gemm_phase(PG8_LAS unsigned char* lds, const Gemm g, const Sched& S, const Epi& E) {
;     ...
;         for (int t = 0; t < nt; t += 2) {
;             const bool last = (t == nt - 2);
;             const char* a1 = cA + (size_t)(t + 1) * kstep;
;             const char* a2 = last ? nA : cA + (size_t)(t + 2) * kstep; const char* b2 = last ? nB : cB + (size_t)(t + 2) * kstep;
;     ...
;             PG8_LDA(At, 1, 1); PG8_STAGE(PG8_SB(1, 0), b3, voffB); PG8_STAGE(PG8_SB(1, 1), b3 + hstep, voffB); PG8_STAGE(PG8_SA(1, 0), a3, voffA);
;             PG8_WAIT_V(8); PG8_WAIT_L(0); PG8_BAR; PG8_MMA(1, 0, At, B0); PG8_MMA(1, 1, At, B1); PG8_BAR; PG8_SCHED;
	s_add_i32 s28, s48, s35
	v_lshl_add_u64 v[156:157], v[156:157], 0, s[10:11]
	s_mov_b32 m0, s28
	ds_read_b128 v[186:189], v162 offset:49152
	ds_read_b128 v[190:193], v162 offset:50176
	ds_read_b128 v[194:197], v162 offset:51200
	ds_read_b128 v[198:201], v162 offset:52224
	ds_read_b128 v[202:205], v162 offset:53248
	ds_read_b128 v[206:209], v162 offset:54272
	ds_read_b128 v[210:213], v162 offset:55296
	ds_read_b128 v[214:217], v162 offset:56320
	global_load_lds_dwordx4 v[156:157], off
	s_add_i32 m0, s28, 0x2000
	s_add_u32 s26, s26, 0xb0080
	v_lshl_add_u64 v[156:157], v[218:219], 0, s[10:11]
	s_addc_u32 s27, s27, 0
	s_add_i32 s28, s49, s35
	global_load_lds_dwordx4 v[156:157], off
	v_lshl_add_u64 v[156:157], s[26:27], 0, v[130:131]
	s_mov_b32 m0, s28
	s_nop 0
	global_load_lds_dwordx4 v[156:157], off
	v_lshl_add_u64 v[156:157], s[26:27], 0, v[134:135]
	s_add_i32 m0, s28, 0x2000
	s_nop 0
	global_load_lds_dwordx4 v[156:157], off
	v_lshl_add_u64 v[156:157], v[220:221], 0, s[10:11]
	s_mov_b32 m0, s42
	s_nop 0
	global_load_lds_dwordx4 v[156:157], off
	v_lshl_add_u64 v[156:157], v[222:223], 0, s[10:11]
	s_mov_b32 m0, s43
	s_nop 0
	global_load_lds_dwordx4 v[156:157], off
	s_waitcnt vmcnt(8)
	s_waitcnt lgkmcnt(0)
	s_barrier
	s_setprio 1
	s_waitcnt lgkmcnt(0)
	v_mfma_f32_16x16x32_bf16 v[60:63], v[144:147], v[186:189], v[60:63]
	v_mfma_f32_16x16x32_bf16 v[56:59], v[152:155], v[186:189], v[56:59]
	v_mfma_f32_16x16x32_bf16 v[44:47], v[144:147], v[194:197], v[44:47]
	v_mfma_f32_16x16x32_bf16 v[40:43], v[152:155], v[194:197], v[40:43]
	v_mfma_f32_16x16x32_bf16 v[28:31], v[144:147], v[202:205], v[28:31]
	v_mfma_f32_16x16x32_bf16 v[24:27], v[152:155], v[202:205], v[24:27]
	v_mfma_f32_16x16x32_bf16 v[12:15], v[144:147], v[210:213], v[12:15]
	v_mfma_f32_16x16x32_bf16 v[8:11], v[152:155], v[210:213], v[8:11]
	v_mfma_f32_16x16x32_bf16 v[60:63], v[148:151], v[190:193], v[60:63]
	v_mfma_f32_16x16x32_bf16 v[56:59], v[166:169], v[190:193], v[56:59]
	v_mfma_f32_16x16x32_bf16 v[44:47], v[148:151], v[198:201], v[44:47]
	v_mfma_f32_16x16x32_bf16 v[40:43], v[166:169], v[198:201], v[40:43]
	v_mfma_f32_16x16x32_bf16 v[28:31], v[148:151], v[206:209], v[28:31]
	v_mfma_f32_16x16x32_bf16 v[24:27], v[166:169], v[206:209], v[24:27]
	v_mfma_f32_16x16x32_bf16 v[12:15], v[148:151], v[214:217], v[12:15]
	v_mfma_f32_16x16x32_bf16 v[8:11], v[166:169], v[214:217], v[8:11]
	s_setprio 0
	s_setprio 1
	v_mfma_f32_16x16x32_bf16 v[52:55], v[170:173], v[186:189], v[52:55]
	v_mfma_f32_16x16x32_bf16 v[48:51], v[178:181], v[186:189], v[48:51]
	v_mfma_f32_16x16x32_bf16 v[36:39], v[170:173], v[194:197], v[36:39]
	v_mfma_f32_16x16x32_bf16 v[32:35], v[178:181], v[194:197], v[32:35]
	v_mfma_f32_16x16x32_bf16 v[20:23], v[170:173], v[202:205], v[20:23]
	v_mfma_f32_16x16x32_bf16 v[16:19], v[178:181], v[202:205], v[16:19]
	v_mfma_f32_16x16x32_bf16 v[4:7], v[170:173], v[210:213], v[4:7]
	v_mfma_f32_16x16x32_bf16 v[0:3], v[178:181], v[210:213], v[0:3]
	v_mfma_f32_16x16x32_bf16 v[52:55], v[174:177], v[190:193], v[52:55]
	v_mfma_f32_16x16x32_bf16 v[48:51], v[182:185], v[190:193], v[48:51]
	v_mfma_f32_16x16x32_bf16 v[36:39], v[174:177], v[198:201], v[36:39]
	v_mfma_f32_16x16x32_bf16 v[32:35], v[182:185], v[198:201], v[32:35]
	v_mfma_f32_16x16x32_bf16 v[20:23], v[174:177], v[206:209], v[20:23]
	v_mfma_f32_16x16x32_bf16 v[16:19], v[182:185], v[206:209], v[16:19]
	v_mfma_f32_16x16x32_bf16 v[4:7], v[174:177], v[214:217], v[4:7]
	v_mfma_f32_16x16x32_bf16 v[0:3], v[182:185], v[214:217], v[0:3]
	s_setprio 0
	s_barrier
	s_add_i32 s55, s55, 2
	s_add_u32 s24, s24, 0x100
	s_addc_u32 s25, s25, 0
	s_add_u32 s53, s53, 0x100
	s_addc_u32 s54, s54, 0
	s_cmp_gt_u32 s55, 41
	s_cbranch_scc0 .LBB0_2271
	s_nop 0
	s_and_b64 vcc, exec, s[12:13]
	s_cbranch_vccz .LBB0_2274
	s_barrier
